# row phases: first row's loads issued before the modulation-vector prologue
# baseline (speedup 1.0000x reference)
; __device__ __forceinline__ void p1a_rows(const Args& A, char* lds, int G) {
;     ...
;         __syncthreads();
; #pragma unroll 1
;         for (int col = tid; col < 1024; col += NTHR) { mv[col] = A.in[I_PREG][col] * (1.f + mod_val(modp, A.in[I_ADAB], 0, b, 1024 + col)); mv[1024 + col] = mod_val(modp, A.in[I_ADAB], 0, b, col); }
;         __syncthreads();
;         f32x4 mul[4], add[4];
; #pragma unroll
;         for (int j = 0; j < 4; ++j) { mul[j] = *(const f32x4*)(mv + 4 * lane + 256 * j); add[j] = *(const f32x4*)(mv + 1024 + 4 * lane + 256 * j); }
;         f32x4 nx[4];
;         { const f32x4* xr = (const f32x4*)(A.in[I_X] + (size_t)(rb * 64 + wave * 8) * DMOD) + lane;
; #pragma unroll
;           for (int j = 0; j < 4; ++j) nx[j] = __builtin_nontemporal_load(&xr[64 * j]); }
.LBB0_383:
	s_barrier
	v_lshl_add_u32 v118, s19, 6, v81
	v_ashrrev_i32_e32 v119, 31, v118
	v_lshlrev_b64 v[118:119], 12, v[118:119]
	v_lshl_add_u64 v[118:119], v[64:65], 0, v[118:119]
	flat_load_dwordx4 v[44:47], v[118:119] nt
	flat_load_dwordx4 v[40:43], v[118:119] offset:1024 nt
	flat_load_dwordx4 v[36:39], v[118:119] offset:2048 nt
	flat_load_dwordx4 v[32:35], v[118:119] offset:3072 nt
	s_and_saveexec_b64 s[6:7], s[4:5]
	s_cbranch_execz .LBB0_386
	s_ashr_i32 s10, s19, 5
	v_mad_i64_i32 v[0:1], s[8:9], s10, v86, v[68:69]
	v_mad_i64_i32 v[2:3], s[8:9], s10, v86, v[72:73]
	s_mov_b64 s[8:9], 0
	s_mov_b64 s[10:11], 0
	v_mov_b32_e32 v4, v83
	v_mov_b32_e32 v5, v82
.LBB0_385:
	v_lshl_add_u64 v[8:9], v[70:71], 0, s[10:11]
	v_lshl_add_u64 v[10:11], v[0:1], 0, s[10:11]
	flat_load_dword v24, v[8:9]
	flat_load_dword v25, v[10:11]
	v_add_co_u32_e32 v8, vcc, 0x30000, v10
	v_lshl_add_u64 v[6:7], v[76:77], 0, s[10:11]
	s_nop 0
	v_addc_co_u32_e32 v9, vcc, 0, v11, vcc
	v_add_co_u32_e32 v12, vcc, 0x60000, v10
	flat_load_dword v26, v[8:9]
	s_nop 0
	v_addc_co_u32_e32 v13, vcc, 0, v11, vcc
	v_add_co_u32_e32 v8, vcc, 0x90000, v10
	v_add_u32_e32 v5, 0x200, v5
	s_nop 0
	v_addc_co_u32_e32 v9, vcc, 0, v11, vcc
	v_add_co_u32_e32 v14, vcc, 0xc0000, v10
	flat_load_dword v27, v[12:13]
	flat_load_dword v28, v[8:9]
	v_addc_co_u32_e32 v15, vcc, 0, v11, vcc
	v_add_co_u32_e32 v8, vcc, 0xf0000, v10
	s_nop 0
	s_nop 0
	v_addc_co_u32_e32 v9, vcc, 0, v11, vcc
	v_add_co_u32_e32 v12, vcc, 0x120000, v10
	flat_load_dword v29, v[14:15]
	flat_load_dword v30, v[8:9]
	v_addc_co_u32_e32 v13, vcc, 0, v11, vcc
	v_add_co_u32_e32 v8, vcc, 0x150000, v10
	s_nop 0
	s_nop 0
	v_addc_co_u32_e32 v9, vcc, 0, v11, vcc
	flat_load_dword v31, v[12:13]
	flat_load_dword v115, v[8:9]
	flat_load_dword v116, v[6:7]
	v_lshl_add_u64 v[8:9], v[2:3], 0, s[10:11]
	v_add_co_u32_e32 v10, vcc, s1, v8
	s_nop 0
	s_nop 0
	v_addc_co_u32_e32 v11, vcc, 0, v9, vcc
	v_add_co_u32_e32 v12, vcc, s3, v8
	s_nop 0
	s_nop 0
	v_addc_co_u32_e32 v13, vcc, 0, v9, vcc
	v_add_co_u32_e32 v14, vcc, s12, v8
	v_lshl_add_u64 v[6:7], v[74:75], 0, s[10:11]
	s_nop 0
	v_addc_co_u32_e32 v15, vcc, 0, v9, vcc
	v_add_co_u32_e32 v16, vcc, s13, v8
	s_add_u32 s10, s10, 0x800
	s_nop 0
	v_addc_co_u32_e32 v17, vcc, 0, v9, vcc
	v_add_co_u32_e32 v18, vcc, s14, v8
	s_addc_u32 s11, s11, 0
	s_nop 0
	v_addc_co_u32_e32 v19, vcc, 0, v9, vcc
	v_add_co_u32_e32 v20, vcc, s15, v8
	s_nop 0
	s_nop 0
	s_nop 0
	v_addc_co_u32_e32 v21, vcc, 0, v9, vcc
	v_add_co_u32_e32 v22, vcc, s16, v8
	s_nop 0
	s_nop 0
	s_nop 0
	s_nop 0
	s_nop 0
	v_addc_co_u32_e32 v23, vcc, 0, v9, vcc
	flat_load_dword v106, v[6:7]
	flat_load_dword v107, v[8:9]
	flat_load_dword v108, v[10:11]
	flat_load_dword v109, v[12:13]
	flat_load_dword v110, v[14:15]
	flat_load_dword v111, v[16:17]
	flat_load_dword v112, v[18:19]
	flat_load_dword v113, v[20:21]
	flat_load_dword v114, v[22:23]
	v_cmp_lt_i32_e32 vcc, s17, v5
	s_or_b64 s[8:9], vcc, s[8:9]
	v_lshl_add_u64 v[8:9], v[70:71], 0, s[10:11]
	v_lshl_add_u64 v[10:11], v[0:1], 0, s[10:11]
	flat_load_dword v87, v[8:9]
	flat_load_dword v88, v[10:11]
	v_add_co_u32_e32 v8, vcc, 0x30000, v10
	v_lshl_add_u64 v[6:7], v[76:77], 0, s[10:11]
	s_nop 0
	v_addc_co_u32_e32 v9, vcc, 0, v11, vcc
	v_add_co_u32_e32 v12, vcc, 0x60000, v10
	flat_load_dword v89, v[8:9]
	s_nop 0
	v_addc_co_u32_e32 v13, vcc, 0, v11, vcc
	v_add_co_u32_e32 v8, vcc, 0x90000, v10
	v_add_u32_e32 v5, 0x200, v5
	s_nop 0
	v_addc_co_u32_e32 v9, vcc, 0, v11, vcc
	v_add_co_u32_e32 v14, vcc, 0xc0000, v10
	flat_load_dword v90, v[12:13]
	flat_load_dword v91, v[8:9]
	v_addc_co_u32_e32 v15, vcc, 0, v11, vcc
	v_add_co_u32_e32 v8, vcc, 0xf0000, v10
	s_nop 0
	s_nop 0
	v_addc_co_u32_e32 v9, vcc, 0, v11, vcc
	v_add_co_u32_e32 v12, vcc, 0x120000, v10
	flat_load_dword v92, v[14:15]
	flat_load_dword v93, v[8:9]
	v_addc_co_u32_e32 v13, vcc, 0, v11, vcc
	v_add_co_u32_e32 v8, vcc, 0x150000, v10
	s_nop 0
	s_nop 0
	v_addc_co_u32_e32 v9, vcc, 0, v11, vcc
	flat_load_dword v94, v[12:13]
	flat_load_dword v95, v[8:9]
	flat_load_dword v96, v[6:7]
	v_lshl_add_u64 v[8:9], v[2:3], 0, s[10:11]
	v_add_co_u32_e32 v10, vcc, s1, v8
	s_nop 0
	s_nop 0
	v_addc_co_u32_e32 v11, vcc, 0, v9, vcc
	v_add_co_u32_e32 v12, vcc, s3, v8
	s_nop 0
	s_nop 0
	v_addc_co_u32_e32 v13, vcc, 0, v9, vcc
	v_add_co_u32_e32 v14, vcc, s12, v8
	v_lshl_add_u64 v[6:7], v[74:75], 0, s[10:11]
	s_nop 0
	v_addc_co_u32_e32 v15, vcc, 0, v9, vcc
	v_add_co_u32_e32 v16, vcc, s13, v8
	s_add_u32 s10, s10, 0x800
	s_nop 0
	v_addc_co_u32_e32 v17, vcc, 0, v9, vcc
	v_add_co_u32_e32 v18, vcc, s14, v8
	s_addc_u32 s11, s11, 0
	s_nop 0
	v_addc_co_u32_e32 v19, vcc, 0, v9, vcc
	v_add_co_u32_e32 v20, vcc, s15, v8
	s_nop 0
	s_nop 0
	s_nop 0
	v_addc_co_u32_e32 v21, vcc, 0, v9, vcc
	v_add_co_u32_e32 v22, vcc, s16, v8
	s_nop 0
	s_nop 0
	s_nop 0
	s_nop 0
	s_nop 0
	v_addc_co_u32_e32 v23, vcc, 0, v9, vcc
	flat_load_dword v97, v[6:7]
	flat_load_dword v98, v[8:9]
	flat_load_dword v99, v[10:11]
	flat_load_dword v100, v[12:13]
	flat_load_dword v101, v[14:15]
	flat_load_dword v102, v[16:17]
	flat_load_dword v103, v[18:19]
	flat_load_dword v104, v[20:21]
	flat_load_dword v105, v[22:23]
	v_cmp_lt_i32_e32 vcc, s17, v5
	s_or_b64 s[8:9], vcc, s[8:9]
	s_waitcnt vmcnt(0) lgkmcnt(0)
	v_add_f32_e32 v24, v24, v25
	v_add_f32_e32 v24, v24, v26
	v_add_f32_e32 v24, v24, v27
	v_add_f32_e32 v24, v24, v28
	v_add_f32_e32 v24, v24, v29
	v_add_f32_e32 v24, v24, v30
	v_add_f32_e32 v24, v24, v31
	v_add_f32_e32 v24, v24, v115
	v_add_f32_e32 v24, 1.0, v24
	v_mul_f32_e32 v24, v116, v24
	ds_write_b32 v4, v24
	v_add_f32_e32 v6, v106, v107
	v_add_f32_e32 v6, v6, v108
	v_add_f32_e32 v6, v6, v109
	v_add_f32_e32 v6, v6, v110
	v_add_f32_e32 v6, v6, v111
	v_add_f32_e32 v6, v6, v112
	v_add_f32_e32 v6, v6, v113
	v_add_f32_e32 v6, v6, v114
	ds_write_b32 v4, v6 offset:4096
	v_add_u32_e32 v4, 0x800, v4
	v_add_f32_e32 v87, v87, v88
	v_add_f32_e32 v87, v87, v89
	v_add_f32_e32 v87, v87, v90
	v_add_f32_e32 v87, v87, v91
	v_add_f32_e32 v87, v87, v92
	v_add_f32_e32 v87, v87, v93
	v_add_f32_e32 v87, v87, v94
	v_add_f32_e32 v87, v87, v95
	v_add_f32_e32 v87, 1.0, v87
	v_mul_f32_e32 v87, v96, v87
	ds_write_b32 v4, v87
	v_add_f32_e32 v6, v97, v98
	v_add_f32_e32 v6, v6, v99
	v_add_f32_e32 v6, v6, v100
	v_add_f32_e32 v6, v6, v101
	v_add_f32_e32 v6, v6, v102
	v_add_f32_e32 v6, v6, v103
	v_add_f32_e32 v6, v6, v104
	v_add_f32_e32 v6, v6, v105
	ds_write_b32 v4, v6 offset:4096
	v_add_u32_e32 v4, 0x800, v4
.LBB0_386:
	s_or_b64 exec, exec, s[6:7]
	v_lshl_add_u32 v0, s19, 6, v81
	v_ashrrev_i32_e32 v1, 31, v0
	v_lshlrev_b64 v[0:1], 12, v[0:1]
	v_lshl_add_u64 v[0:1], v[64:65], 0, v[0:1]
	s_waitcnt lgkmcnt(0)
	s_barrier
	ds_read_b128 v[0:3], v80
	ds_read_b128 v[4:7], v80 offset:1024
	ds_read_b128 v[8:11], v80 offset:4096
	ds_read_b128 v[12:15], v80 offset:5120
	ds_read_b128 v[16:19], v80 offset:2048
	ds_read_b128 v[20:23], v80 offset:3072
	ds_read_b128 v[24:27], v80 offset:6144
	ds_read_b128 v[28:31], v80 offset:7168
	s_mov_b32 s6, 0
	s_branch .LBB0_388

; __device__ __forceinline__ void p3b_rows(const Args& A, char* lds, int G) {
;     ...
;         { const int m = rb * 64 + wave * 8; const f32x4* xr = (const f32x4*)(A.in[I_X] + (size_t)m * DMOD) + lane; const v2u* yr = (const v2u*)((unsigned char*)A.out + (size_t)m * 4096) + lane;
; #pragma unroll
;           for (int j = 0; j < 4; ++j) { nx[j] = __builtin_nontemporal_load(&xr[64 * j]); ny[j] = yr[64 * j]; } }
.LBB0_1171:
	s_barrier
	v_lshl_add_u32 v200, s26, 6, v122
	v_ashrrev_i32_e32 v201, 31, v200
	v_lshlrev_b64 v[200:201], 12, v[200:201]
	v_lshl_add_u64 v[202:203], v[84:85], 0, v[200:201]
	v_lshl_add_u64 v[200:201], v[86:87], 0, v[200:201]
	flat_load_dwordx4 v[76:79], v[202:203] nt
	flat_load_dwordx4 v[72:75], v[202:203] offset:1024 nt
	flat_load_dwordx2 v[118:119], v[200:201]
	flat_load_dwordx2 v[116:117], v[200:201] offset:512
	flat_load_dwordx2 v[114:115], v[200:201] offset:1024
	flat_load_dwordx2 v[112:113], v[200:201] offset:1536
	flat_load_dwordx4 v[68:71], v[202:203] offset:2048 nt
	flat_load_dwordx4 v[52:55], v[202:203] offset:3072 nt
	s_and_saveexec_b64 s[12:13], s[6:7]
	s_cbranch_execz .LBB0_1174
	s_ashr_i32 s16, s26, 5
	v_mad_i64_i32 v[0:1], s[14:15], s16, v127, v[88:89]
	v_mad_i64_i32 v[2:3], s[14:15], s16, v127, v[92:93]
	v_mad_i64_i32 v[4:5], s[14:15], s16, v127, v[96:97]
	s_mov_b64 s[14:15], 0
	v_mov_b32_e32 v6, v124
	s_mov_b64 s[16:17], 0
	v_mov_b32_e32 v7, v123

; __device__ __forceinline__ void p3b_rows(const Args& A, char* lds, int G) {
;     ...
;         for (int j = 0; j < 4; ++j) { g0[j] = *(const f32x4*)(mv + 4 * lane + 256 * j); mul[j] = *(const f32x4*)(mv + 1024 + 4 * lane + 256 * j); add[j] = *(const f32x4*)(mv + 2048 + 4 * lane + 256 * j); }
;         f32x4 nx[4]; v2u ny[4];
;         { const int m = rb * 64 + wave * 8; const f32x4* xr = (const f32x4*)(A.in[I_X] + (size_t)m * DMOD) + lane; const v2u* yr = (const v2u*)((unsigned char*)A.out + (size_t)m * 4096) + lane;
; #pragma unroll
;           for (int j = 0; j < 4; ++j) { nx[j] = __builtin_nontemporal_load(&xr[64 * j]); ny[j] = yr[64 * j]; } }
.LBB0_1174:
	s_or_b64 exec, exec, s[12:13]
	v_lshl_add_u32 v0, s26, 6, v122
	v_ashrrev_i32_e32 v1, 31, v0
	v_lshlrev_b64 v[0:1], 12, v[0:1]
	v_lshl_add_u64 v[2:3], v[84:85], 0, v[0:1]
	s_waitcnt lgkmcnt(0)
	s_barrier
	v_lshl_add_u64 v[0:1], v[86:87], 0, v[0:1]
	ds_read_b128 v[0:3], v81
	ds_read_b128 v[4:7], v81 offset:1024
	ds_read_b128 v[8:11], v81 offset:4096
	ds_read_b128 v[12:15], v81 offset:5120
	ds_read_b128 v[16:19], v81 offset:8192
	ds_read_b128 v[20:23], v81 offset:9216
	ds_read_b128 v[24:27], v81 offset:2048
	ds_read_b128 v[28:31], v81 offset:3072
	ds_read_b128 v[32:35], v81 offset:6144
	ds_read_b128 v[36:39], v81 offset:7168
	ds_read_b128 v[40:43], v81 offset:10240
	ds_read_b128 v[44:47], v81 offset:11264
	s_mov_b32 s12, 0
	s_waitcnt vmcnt(0) lgkmcnt(0)
	v_mov_b64_e32 v[102:103], v[118:119]
	v_mov_b64_e32 v[104:105], v[116:117]
	v_mov_b64_e32 v[106:107], v[114:115]
	v_mov_b64_e32 v[108:109], v[112:113]
	s_branch .LBB0_1176

; __device__ __forceinline__ void p6b_rows(const Args& A, char* lds, int G) {
;     ...
;         { const int m = rb * 64 + wave * 8; const f32x4* xr = (const f32x4*)(A.in[I_X] + (size_t)m * DMOD) + lane; const v2u* y1r = (const v2u*)((unsigned char*)A.out + (size_t)m * 4096) + lane;
; #pragma unroll
;           for (int j = 0; j < 4; ++j) { nx[j] = __builtin_nontemporal_load(&xr[64 * j]); n0[j] = y1r[64 * j]; n1[j] = y1r[256 + 64 * j]; } }
.LBB0_1648:
	s_barrier
	v_lshl_add_u32 v200, s2, 6, v81
	v_ashrrev_i32_e32 v201, 31, v200
	v_lshlrev_b64 v[200:201], 12, v[200:201]
	v_lshl_add_u64 v[202:203], v[68:69], 0, v[200:201]
	v_lshl_add_u64 v[200:201], v[70:71], 0, v[200:201]
	flat_load_dwordx2 v[110:111], v[200:201] offset:2048
	flat_load_dwordx2 v[108:109], v[200:201] offset:2560
	flat_load_dwordx2 v[104:105], v[200:201] offset:3072
	flat_load_dwordx2 v[102:103], v[200:201] offset:3584
	flat_load_dwordx2 v[114:115], v[200:201]
	flat_load_dwordx2 v[112:113], v[200:201] offset:512
	flat_load_dwordx2 v[100:101], v[200:201] offset:1024
	flat_load_dwordx2 v[106:107], v[200:201] offset:1536
	flat_load_dwordx4 v[60:63], v[202:203] nt
	flat_load_dwordx4 v[56:59], v[202:203] offset:1024 nt
	flat_load_dwordx4 v[52:55], v[202:203] offset:2048 nt
	flat_load_dwordx4 v[44:47], v[202:203] offset:3072 nt
	s_and_saveexec_b64 s[4:5], s[0:1]
	s_cbranch_execz .LBB0_1651
	s_ashr_i32 s12, s2, 5
	v_mad_i64_i32 v[0:1], s[12:13], s12, v121, v[72:73]
	s_mov_b64 s[12:13], 0
	s_mov_b64 s[14:15], 0
	v_mov_b32_e32 v2, v119
	v_mov_b32_e32 v3, v118

; __device__ __forceinline__ void p6b_rows(const Args& A, char* lds, int G) {
;     ...
;         for (int j = 0; j < 4; ++j) { g0[j] = *(const f32x4*)(mv + 4 * lane + 256 * j); g1[j] = *(const f32x4*)(mv + 1024 + 4 * lane + 256 * j); }
;         f32x4 nx[4]; v2u n0[4], n1[4];
;         { const int m = rb * 64 + wave * 8; const f32x4* xr = (const f32x4*)(A.in[I_X] + (size_t)m * DMOD) + lane; const v2u* y1r = (const v2u*)((unsigned char*)A.out + (size_t)m * 4096) + lane;
; #pragma unroll
;           for (int j = 0; j < 4; ++j) { nx[j] = __builtin_nontemporal_load(&xr[64 * j]); n0[j] = y1r[64 * j]; n1[j] = y1r[256 + 64 * j]; } }
.LBB0_1651:
	s_or_b64 exec, exec, s[4:5]
	v_lshl_add_u32 v0, s2, 6, v81
	v_ashrrev_i32_e32 v1, 31, v0
	v_lshlrev_b64 v[0:1], 12, v[0:1]
	v_lshl_add_u64 v[2:3], v[68:69], 0, v[0:1]
	v_lshl_add_u64 v[0:1], v[70:71], 0, v[0:1]
	s_waitcnt lgkmcnt(0)
	s_barrier
	ds_read_b128 v[0:3], v65
	ds_read_b128 v[4:7], v65 offset:1024
	ds_read_b128 v[8:11], v65 offset:4096
	ds_read_b128 v[12:15], v65 offset:5120
	ds_read_b128 v[16:19], v65 offset:2048
	ds_read_b128 v[20:23], v65 offset:3072
	ds_read_b128 v[24:27], v65 offset:6144
	ds_read_b128 v[28:31], v65 offset:7168
	s_mov_b32 s12, 0
	s_waitcnt vmcnt(0) lgkmcnt(0)
	v_mov_b64_e32 v[82:83], v[110:111]
	v_mov_b64_e32 v[84:85], v[108:109]
	v_mov_b64_e32 v[88:89], v[104:105]
	v_mov_b64_e32 v[94:95], v[102:103]
	v_mov_b64_e32 v[90:91], v[114:115]
	v_mov_b64_e32 v[86:87], v[112:113]
	v_mov_b64_e32 v[92:93], v[100:101]
	v_mov_b64_e32 v[96:97], v[106:107]
	v_mov_b64_e32 v[32:33], v[60:61]
	v_mov_b64_e32 v[36:37], v[56:57]
	v_mov_b64_e32 v[40:41], v[52:53]
	v_mov_b64_e32 v[50:51], v[46:47]
	v_mov_b64_e32 v[34:35], v[62:63]
	v_mov_b64_e32 v[38:39], v[58:59]
	v_mov_b64_e32 v[42:43], v[54:55]
	v_mov_b64_e32 v[48:49], v[44:45]
	s_branch .LBB0_1653
